# pool_pre rewritten around the wave-uniform window (static ring registers per w, constant 1/cnt), on top of v43
# baseline (speedup 1.0000x reference)
; __device__ __forceinline__ float bflo(unsigned u) { return __uint_as_float(u << 16); }
; __device__ __forceinline__ float bfhi(unsigned u) { return __uint_as_float(u & 0xffff0000u); }
; __device__ __forceinline__ void pool_pre_phase(const bf16_t* hn, bf16_t* yp, int gtid, int ngt) {
;     for (int idx = gtid; idx < NB * (SEQ / 64) * (DM / 2); idx += ngt) {
;         const int cp = idx & 1023, run = idx >> 10, col = cp * 2, g = col >> 9, w = 2 << g;
;         const int tr0 = (run & 63) * 64;
;         const size_t row0 = (size_t)run * 64;
;         const bf16_t* p = hn + row0 * DM + col;
;         float r0[16], r1[16]; float s0 = 0.f, s1 = 0.f;
; #pragma unroll
;         for (int i = 0; i < 16; ++i) { r0[i] = 0.f; r1[i] = 0.f; }
;         if (tr0 > 0) {
; #pragma unroll
;             for (int i = 1; i < 16; ++i) { const unsigned v = *(const unsigned*)(p - (size_t)(16 - i) * DM); r0[i] = bflo(v); r1[i] = bfhi(v);
;                 if (16 - i <= w) { s0 += r0[i]; s1 += r1[i]; } }
;         }
.LBB0_433:
	s_andn2_b64 vcc, exec, s[0:1]
	s_cbranch_vccnz .LBB0_507
	v_mov_b32_e32 v0, v175
	v_readlane_b32 s0, v254, 6
	s_mov_b64 s[30:31], s[60:61]
	s_nop 0
	v_add_u32_e32 v9, s0, v0
	s_mov_b32 s0, 0x40000
	v_cmp_gt_i32_e32 vcc, s0, v9
	s_and_saveexec_b64 s[36:37], vcc
	s_cbranch_execz .LBB0_441
	s_mov_b64 s[20:21], 0
	v_and_b32_e32 v10, 63, v175
	v_lshlrev_b32_e32 v10, 2, v10
.Lpp_item:
	v_readfirstlane_b32 s0, v9
	s_lshr_b32 s1, s0, 10
	s_and_b32 s6, s0, 0x3ff
	s_lshr_b32 s56, s6, 8
	s_and_b32 s60, s1, 63
	s_lshl_b32 s1, s1, 18
	s_lshl_b32 s6, s6, 2
	s_add_u32 s1, s1, s6
	s_add_u32 s62, s1, 0x16c00000
	s_add_u32 s62, s90, s62
	s_addc_u32 s63, s91, 0
	s_add_u32 s64, s1, 0x40500000
	s_add_u32 s64, s90, s64
	s_addc_u32 s65, s91, 0
	s_cmp_eq_u32 s56, 0
	s_cbranch_scc1 .Lpp_w2
	s_cmp_eq_u32 s56, 1
	s_cbranch_scc1 .Lpp_w4
	s_cmp_eq_u32 s56, 2
	s_cbranch_scc1 .Lpp_w8
	s_branch .Lpp_w16
.Lpp_w2:
	s_cmp_eq_u32 s60, 0
	s_cbranch_scc1 .Lpp_w2_zero
	s_sub_u32 s0, s62, 0xf000
	s_subb_u32 s1, s63, 0
	global_load_dword v79, v10, s[0:1]
	s_add_u32 s0, s0, 0x1000
	s_addc_u32 s1, s1, 0
	global_load_dword v80, v10, s[0:1]
	s_add_u32 s0, s0, 0x1000
	s_addc_u32 s1, s1, 0
	global_load_dword v81, v10, s[0:1]
	s_add_u32 s0, s0, 0x1000
	s_addc_u32 s1, s1, 0
	global_load_dword v82, v10, s[0:1]
	s_add_u32 s0, s0, 0x1000
	s_addc_u32 s1, s1, 0
	global_load_dword v83, v10, s[0:1]
	s_add_u32 s0, s0, 0x1000
	s_addc_u32 s1, s1, 0
	global_load_dword v84, v10, s[0:1]
	s_add_u32 s0, s0, 0x1000
	s_addc_u32 s1, s1, 0
	global_load_dword v85, v10, s[0:1]
	s_add_u32 s0, s0, 0x1000
	s_addc_u32 s1, s1, 0
	global_load_dword v86, v10, s[0:1]
	s_add_u32 s0, s0, 0x1000
	s_addc_u32 s1, s1, 0
	global_load_dword v87, v10, s[0:1]
	s_add_u32 s0, s0, 0x1000
	s_addc_u32 s1, s1, 0
	global_load_dword v88, v10, s[0:1]
	s_add_u32 s0, s0, 0x1000
	s_addc_u32 s1, s1, 0
	global_load_dword v89, v10, s[0:1]
	s_add_u32 s0, s0, 0x1000
	s_addc_u32 s1, s1, 0
	global_load_dword v90, v10, s[0:1]
	s_add_u32 s0, s0, 0x1000
	s_addc_u32 s1, s1, 0
	global_load_dword v91, v10, s[0:1]
	s_add_u32 s0, s0, 0x1000
	s_addc_u32 s1, s1, 0
	global_load_dword v92, v10, s[0:1]
	s_add_u32 s0, s0, 0x1000
	s_addc_u32 s1, s1, 0
	global_load_dword v93, v10, s[0:1]
	s_add_u32 s0, s0, 0x1000
	s_addc_u32 s1, s1, 0
	s_waitcnt vmcnt(0)
	v_mov_b64_e32 v[20:21], 0
	v_mov_b64_e32 v[52:53], 0
	v_lshlrev_b32_e32 v22, 16, v79
	v_and_b32_e32 v23, 0xffff0000, v79
	v_lshlrev_b32_e32 v24, 16, v80
	v_and_b32_e32 v25, 0xffff0000, v80
	v_lshlrev_b32_e32 v26, 16, v81
	v_and_b32_e32 v27, 0xffff0000, v81
	v_lshlrev_b32_e32 v28, 16, v82
	v_and_b32_e32 v29, 0xffff0000, v82
	v_lshlrev_b32_e32 v30, 16, v83
	v_and_b32_e32 v31, 0xffff0000, v83
	v_lshlrev_b32_e32 v32, 16, v84
	v_and_b32_e32 v33, 0xffff0000, v84
	v_lshlrev_b32_e32 v34, 16, v85
	v_and_b32_e32 v35, 0xffff0000, v85
	v_lshlrev_b32_e32 v36, 16, v86
	v_and_b32_e32 v37, 0xffff0000, v86
	v_lshlrev_b32_e32 v38, 16, v87
	v_and_b32_e32 v39, 0xffff0000, v87
	v_lshlrev_b32_e32 v40, 16, v88
	v_and_b32_e32 v41, 0xffff0000, v88
	v_lshlrev_b32_e32 v42, 16, v89
	v_and_b32_e32 v43, 0xffff0000, v89
	v_lshlrev_b32_e32 v44, 16, v90
	v_and_b32_e32 v45, 0xffff0000, v90
	v_lshlrev_b32_e32 v46, 16, v91
	v_and_b32_e32 v47, 0xffff0000, v91
	v_lshlrev_b32_e32 v48, 16, v92
	v_and_b32_e32 v49, 0xffff0000, v92
	v_lshlrev_b32_e32 v50, 16, v93
	v_and_b32_e32 v51, 0xffff0000, v93
	v_pk_add_f32 v[52:53], v[52:53], v[48:49]
	v_pk_add_f32 v[52:53], v[52:53], v[50:51]
	s_branch .Lpp_w2_go
.Lpp_w2_zero:
	v_mov_b64_e32 v[20:21], 0
	v_mov_b64_e32 v[22:23], 0
	v_mov_b64_e32 v[24:25], 0
	v_mov_b64_e32 v[26:27], 0
	v_mov_b64_e32 v[28:29], 0
	v_mov_b64_e32 v[30:31], 0
	v_mov_b64_e32 v[32:33], 0
	v_mov_b64_e32 v[34:35], 0
	v_mov_b64_e32 v[36:37], 0
	v_mov_b64_e32 v[38:39], 0
	v_mov_b64_e32 v[40:41], 0
	v_mov_b64_e32 v[42:43], 0
	v_mov_b64_e32 v[44:45], 0
	v_mov_b64_e32 v[46:47], 0
	v_mov_b64_e32 v[48:49], 0
	v_mov_b64_e32 v[50:51], 0
	v_mov_b64_e32 v[52:53], 0
.Lpp_w2_go:
	s_mov_b32 s61, 0
.Lpp_w2_blk:
	s_mov_b32 s40, 0x3f000000
	s_mov_b32 s41, 0x3f000000
	s_mov_b32 s42, 0x3f000000
	s_mov_b32 s43, 0x3f000000
	s_mov_b32 s44, 0x3f000000
	s_mov_b32 s45, 0x3f000000
	s_mov_b32 s46, 0x3f000000
	s_mov_b32 s47, 0x3f000000
	s_mov_b32 s48, 0x3f000000
	s_mov_b32 s49, 0x3f000000
	s_mov_b32 s50, 0x3f000000
	s_mov_b32 s51, 0x3f000000
	s_mov_b32 s52, 0x3f000000
	s_mov_b32 s53, 0x3f000000
	s_mov_b32 s54, 0x3f000000
	s_mov_b32 s55, 0x3f000000
	s_or_b32 s66, s60, s61
	s_cmp_lg_u32 s66, 0
	s_cbranch_scc1 .Lpp_w2_ld
	s_mov_b32 s40, 0x3f800000
; __device__ __forceinline__ unsigned cvtpk(float lo, float hi) { return pg8::cvt_pk_bf16(lo, hi); }
; __device__ __forceinline__ float bflo(unsigned u) { return __uint_as_float(u << 16); }
; __device__ __forceinline__ float bfhi(unsigned u) { return __uint_as_float(u & 0xffff0000u); }
; __device__ __forceinline__ void pool_pre_phase(const bf16_t* hn, bf16_t* yp, int gtid, int ngt) {
;     ...
;         for (int tb = 0; tb < 64; tb += 16) {
; #pragma unroll
;             for (int i = 0; i < 16; ++i) { const int t = tb + i; const unsigned v = *(const unsigned*)(p + (size_t)t * DM);
;                 const float n0 = bflo(v), n1 = bfhi(v);
;                 const float o0 = r0[(i + 16 - w) & 15], o1 = r1[(i + 16 - w) & 15];
;                 s0 += n0 - o0; s1 += n1 - o1; r0[i] = n0; r1[i] = n1;
;                 const int cnt = (tr0 + t + 1 < w) ? (tr0 + t + 1) : w; const float inv = 1.0f / (float)cnt;
;                 *(unsigned*)(yp + (row0 + t) * DM + col) = cvtpk(s0 * inv - n0, s1 * inv - n1); }
.Lpp_w2_ld:
	s_mov_b64 s[0:1], s[62:63]
	global_load_dword v62, v10, s[0:1]
	s_add_u32 s0, s0, 0x1000
	s_addc_u32 s1, s1, 0
	global_load_dword v63, v10, s[0:1]
	s_add_u32 s0, s0, 0x1000
	s_addc_u32 s1, s1, 0
	global_load_dword v64, v10, s[0:1]
	s_add_u32 s0, s0, 0x1000
	s_addc_u32 s1, s1, 0
	global_load_dword v65, v10, s[0:1]
	s_add_u32 s0, s0, 0x1000
	s_addc_u32 s1, s1, 0
	global_load_dword v66, v10, s[0:1]
	s_add_u32 s0, s0, 0x1000
	s_addc_u32 s1, s1, 0
	global_load_dword v67, v10, s[0:1]
	s_add_u32 s0, s0, 0x1000
	s_addc_u32 s1, s1, 0
	global_load_dword v68, v10, s[0:1]
	s_add_u32 s0, s0, 0x1000
	s_addc_u32 s1, s1, 0
	global_load_dword v69, v10, s[0:1]
	s_add_u32 s0, s0, 0x1000
	s_addc_u32 s1, s1, 0
	global_load_dword v70, v10, s[0:1]
	s_add_u32 s0, s0, 0x1000
	s_addc_u32 s1, s1, 0
	global_load_dword v71, v10, s[0:1]
	s_add_u32 s0, s0, 0x1000
	s_addc_u32 s1, s1, 0
	global_load_dword v72, v10, s[0:1]
	s_add_u32 s0, s0, 0x1000
	s_addc_u32 s1, s1, 0
	global_load_dword v73, v10, s[0:1]
	s_add_u32 s0, s0, 0x1000
	s_addc_u32 s1, s1, 0
	global_load_dword v74, v10, s[0:1]
	s_add_u32 s0, s0, 0x1000
	s_addc_u32 s1, s1, 0
	global_load_dword v75, v10, s[0:1]
	s_add_u32 s0, s0, 0x1000
	s_addc_u32 s1, s1, 0
	global_load_dword v76, v10, s[0:1]
	s_add_u32 s0, s0, 0x1000
	s_addc_u32 s1, s1, 0
	global_load_dword v77, v10, s[0:1]
	s_add_u32 s0, s0, 0x1000
	s_addc_u32 s1, s1, 0
	s_mov_b64 s[62:63], s[0:1]
	s_waitcnt vmcnt(15)
	v_lshlrev_b32_e32 v54, 16, v62
	v_and_b32_e32 v55, 0xffff0000, v62
	v_pk_add_f32 v[56:57], v[54:55], v[48:49] neg_lo:[0,1] neg_hi:[0,1]
	v_pk_add_f32 v[52:53], v[52:53], v[56:57]
	v_fma_f32 v58, s40, v52, -v54
	v_fma_f32 v59, s40, v53, -v55
	v_cvt_pk_bf16_f32 v60, v58, v59
	global_store_dword v10, v60, s[64:65]
	s_add_u32 s64, s64, 0x1000
	s_addc_u32 s65, s65, 0
	v_mov_b64_e32 v[20:21], v[54:55]
	s_waitcnt vmcnt(15)
	v_lshlrev_b32_e32 v54, 16, v63
	v_and_b32_e32 v55, 0xffff0000, v63
	v_pk_add_f32 v[56:57], v[54:55], v[50:51] neg_lo:[0,1] neg_hi:[0,1]
	v_pk_add_f32 v[52:53], v[52:53], v[56:57]
	v_fma_f32 v58, s41, v52, -v54
	v_fma_f32 v59, s41, v53, -v55
	v_cvt_pk_bf16_f32 v60, v58, v59
	global_store_dword v10, v60, s[64:65]
	s_add_u32 s64, s64, 0x1000
	s_addc_u32 s65, s65, 0
	v_mov_b64_e32 v[22:23], v[54:55]
	s_waitcnt vmcnt(15)
	v_lshlrev_b32_e32 v54, 16, v64
	v_and_b32_e32 v55, 0xffff0000, v64
	v_pk_add_f32 v[56:57], v[54:55], v[20:21] neg_lo:[0,1] neg_hi:[0,1]
	v_pk_add_f32 v[52:53], v[52:53], v[56:57]
	v_fma_f32 v58, s42, v52, -v54
	v_fma_f32 v59, s42, v53, -v55
	v_cvt_pk_bf16_f32 v60, v58, v59
	global_store_dword v10, v60, s[64:65]
	s_add_u32 s64, s64, 0x1000
	s_addc_u32 s65, s65, 0
	v_mov_b64_e32 v[24:25], v[54:55]
	s_waitcnt vmcnt(15)
	v_lshlrev_b32_e32 v54, 16, v65
	v_and_b32_e32 v55, 0xffff0000, v65
	v_pk_add_f32 v[56:57], v[54:55], v[22:23] neg_lo:[0,1] neg_hi:[0,1]
	v_pk_add_f32 v[52:53], v[52:53], v[56:57]
	v_fma_f32 v58, s43, v52, -v54
	v_fma_f32 v59, s43, v53, -v55
	v_cvt_pk_bf16_f32 v60, v58, v59
	global_store_dword v10, v60, s[64:65]
	s_add_u32 s64, s64, 0x1000
	s_addc_u32 s65, s65, 0
	v_mov_b64_e32 v[26:27], v[54:55]
	s_waitcnt vmcnt(15)
	v_lshlrev_b32_e32 v54, 16, v66
	v_and_b32_e32 v55, 0xffff0000, v66
	v_pk_add_f32 v[56:57], v[54:55], v[24:25] neg_lo:[0,1] neg_hi:[0,1]
	v_pk_add_f32 v[52:53], v[52:53], v[56:57]
	v_fma_f32 v58, s44, v52, -v54
	v_fma_f32 v59, s44, v53, -v55
	v_cvt_pk_bf16_f32 v60, v58, v59
	global_store_dword v10, v60, s[64:65]
	s_add_u32 s64, s64, 0x1000
	s_addc_u32 s65, s65, 0
	v_mov_b64_e32 v[28:29], v[54:55]
	s_waitcnt vmcnt(15)
	v_lshlrev_b32_e32 v54, 16, v67
	v_and_b32_e32 v55, 0xffff0000, v67
	v_pk_add_f32 v[56:57], v[54:55], v[26:27] neg_lo:[0,1] neg_hi:[0,1]
	v_pk_add_f32 v[52:53], v[52:53], v[56:57]
	v_fma_f32 v58, s45, v52, -v54
	v_fma_f32 v59, s45, v53, -v55
	v_cvt_pk_bf16_f32 v60, v58, v59
	global_store_dword v10, v60, s[64:65]
	s_add_u32 s64, s64, 0x1000
	s_addc_u32 s65, s65, 0
	v_mov_b64_e32 v[30:31], v[54:55]
	s_waitcnt vmcnt(15)
	v_lshlrev_b32_e32 v54, 16, v68
	v_and_b32_e32 v55, 0xffff0000, v68
	v_pk_add_f32 v[56:57], v[54:55], v[28:29] neg_lo:[0,1] neg_hi:[0,1]
	v_pk_add_f32 v[52:53], v[52:53], v[56:57]
	v_fma_f32 v58, s46, v52, -v54
	v_fma_f32 v59, s46, v53, -v55
	v_cvt_pk_bf16_f32 v60, v58, v59
	global_store_dword v10, v60, s[64:65]
	s_add_u32 s64, s64, 0x1000
	s_addc_u32 s65, s65, 0
	v_mov_b64_e32 v[32:33], v[54:55]
	s_waitcnt vmcnt(15)
	v_lshlrev_b32_e32 v54, 16, v69
	v_and_b32_e32 v55, 0xffff0000, v69
	v_pk_add_f32 v[56:57], v[54:55], v[30:31] neg_lo:[0,1] neg_hi:[0,1]
	v_pk_add_f32 v[52:53], v[52:53], v[56:57]
	v_fma_f32 v58, s47, v52, -v54
	v_fma_f32 v59, s47, v53, -v55
	v_cvt_pk_bf16_f32 v60, v58, v59
	global_store_dword v10, v60, s[64:65]
	s_add_u32 s64, s64, 0x1000
	s_addc_u32 s65, s65, 0
	v_mov_b64_e32 v[34:35], v[54:55]
	s_waitcnt vmcnt(15)
	v_lshlrev_b32_e32 v54, 16, v70
	v_and_b32_e32 v55, 0xffff0000, v70
	v_pk_add_f32 v[56:57], v[54:55], v[32:33] neg_lo:[0,1] neg_hi:[0,1]
	v_pk_add_f32 v[52:53], v[52:53], v[56:57]
	v_fma_f32 v58, s48, v52, -v54
	v_fma_f32 v59, s48, v53, -v55
	v_cvt_pk_bf16_f32 v60, v58, v59
	global_store_dword v10, v60, s[64:65]
	s_add_u32 s64, s64, 0x1000
	s_addc_u32 s65, s65, 0
	v_mov_b64_e32 v[36:37], v[54:55]
	s_waitcnt vmcnt(15)
	v_lshlrev_b32_e32 v54, 16, v71
	v_and_b32_e32 v55, 0xffff0000, v71
	v_pk_add_f32 v[56:57], v[54:55], v[34:35] neg_lo:[0,1] neg_hi:[0,1]
	v_pk_add_f32 v[52:53], v[52:53], v[56:57]
	v_fma_f32 v58, s49, v52, -v54
	v_fma_f32 v59, s49, v53, -v55
	v_cvt_pk_bf16_f32 v60, v58, v59
	global_store_dword v10, v60, s[64:65]
	s_add_u32 s64, s64, 0x1000
	s_addc_u32 s65, s65, 0
	v_mov_b64_e32 v[38:39], v[54:55]
	s_waitcnt vmcnt(15)
; __device__ __forceinline__ unsigned cvtpk(float lo, float hi) { return pg8::cvt_pk_bf16(lo, hi); }
; __device__ __forceinline__ float bflo(unsigned u) { return __uint_as_float(u << 16); }
; __device__ __forceinline__ float bfhi(unsigned u) { return __uint_as_float(u & 0xffff0000u); }
; __device__ __forceinline__ void pool_pre_phase(const bf16_t* hn, bf16_t* yp, int gtid, int ngt) {
;     ...
;         if (tr0 > 0) {
; #pragma unroll
;             for (int i = 1; i < 16; ++i) { const unsigned v = *(const unsigned*)(p - (size_t)(16 - i) * DM); r0[i] = bflo(v); r1[i] = bfhi(v);
;                 if (16 - i <= w) { s0 += r0[i]; s1 += r1[i]; } }
;         }
;         for (int tb = 0; tb < 64; tb += 16) {
; #pragma unroll
;             for (int i = 0; i < 16; ++i) { const int t = tb + i; const unsigned v = *(const unsigned*)(p + (size_t)t * DM);
;                 const float n0 = bflo(v), n1 = bfhi(v);
;                 const float o0 = r0[(i + 16 - w) & 15], o1 = r1[(i + 16 - w) & 15];
;                 s0 += n0 - o0; s1 += n1 - o1; r0[i] = n0; r1[i] = n1;
;                 const int cnt = (tr0 + t + 1 < w) ? (tr0 + t + 1) : w; const float inv = 1.0f / (float)cnt;
;                 *(unsigned*)(yp + (row0 + t) * DM + col) = cvtpk(s0 * inv - n0, s1 * inv - n1); }
	v_lshlrev_b32_e32 v54, 16, v72
	v_and_b32_e32 v55, 0xffff0000, v72
	v_pk_add_f32 v[56:57], v[54:55], v[36:37] neg_lo:[0,1] neg_hi:[0,1]
	v_pk_add_f32 v[52:53], v[52:53], v[56:57]
	v_fma_f32 v58, s50, v52, -v54
	v_fma_f32 v59, s50, v53, -v55
	v_cvt_pk_bf16_f32 v60, v58, v59
	global_store_dword v10, v60, s[64:65]
	s_add_u32 s64, s64, 0x1000
	s_addc_u32 s65, s65, 0
	v_mov_b64_e32 v[40:41], v[54:55]
	s_waitcnt vmcnt(15)
	v_lshlrev_b32_e32 v54, 16, v73
	v_and_b32_e32 v55, 0xffff0000, v73
	v_pk_add_f32 v[56:57], v[54:55], v[38:39] neg_lo:[0,1] neg_hi:[0,1]
	v_pk_add_f32 v[52:53], v[52:53], v[56:57]
	v_fma_f32 v58, s51, v52, -v54
	v_fma_f32 v59, s51, v53, -v55
	v_cvt_pk_bf16_f32 v60, v58, v59
	global_store_dword v10, v60, s[64:65]
	s_add_u32 s64, s64, 0x1000
	s_addc_u32 s65, s65, 0
	v_mov_b64_e32 v[42:43], v[54:55]
	s_waitcnt vmcnt(15)
	v_lshlrev_b32_e32 v54, 16, v74
	v_and_b32_e32 v55, 0xffff0000, v74
	v_pk_add_f32 v[56:57], v[54:55], v[40:41] neg_lo:[0,1] neg_hi:[0,1]
	v_pk_add_f32 v[52:53], v[52:53], v[56:57]
	v_fma_f32 v58, s52, v52, -v54
	v_fma_f32 v59, s52, v53, -v55
	v_cvt_pk_bf16_f32 v60, v58, v59
	global_store_dword v10, v60, s[64:65]
	s_add_u32 s64, s64, 0x1000
	s_addc_u32 s65, s65, 0
	v_mov_b64_e32 v[44:45], v[54:55]
	s_waitcnt vmcnt(15)
	v_lshlrev_b32_e32 v54, 16, v75
	v_and_b32_e32 v55, 0xffff0000, v75
	v_pk_add_f32 v[56:57], v[54:55], v[42:43] neg_lo:[0,1] neg_hi:[0,1]
	v_pk_add_f32 v[52:53], v[52:53], v[56:57]
	v_fma_f32 v58, s53, v52, -v54
	v_fma_f32 v59, s53, v53, -v55
	v_cvt_pk_bf16_f32 v60, v58, v59
	global_store_dword v10, v60, s[64:65]
	s_add_u32 s64, s64, 0x1000
	s_addc_u32 s65, s65, 0
	v_mov_b64_e32 v[46:47], v[54:55]
	s_waitcnt vmcnt(15)
	v_lshlrev_b32_e32 v54, 16, v76
	v_and_b32_e32 v55, 0xffff0000, v76
	v_pk_add_f32 v[56:57], v[54:55], v[44:45] neg_lo:[0,1] neg_hi:[0,1]
	v_pk_add_f32 v[52:53], v[52:53], v[56:57]
	v_fma_f32 v58, s54, v52, -v54
	v_fma_f32 v59, s54, v53, -v55
	v_cvt_pk_bf16_f32 v60, v58, v59
	global_store_dword v10, v60, s[64:65]
	s_add_u32 s64, s64, 0x1000
	s_addc_u32 s65, s65, 0
	v_mov_b64_e32 v[48:49], v[54:55]
	s_waitcnt vmcnt(15)
	v_lshlrev_b32_e32 v54, 16, v77
	v_and_b32_e32 v55, 0xffff0000, v77
	v_pk_add_f32 v[56:57], v[54:55], v[46:47] neg_lo:[0,1] neg_hi:[0,1]
	v_pk_add_f32 v[52:53], v[52:53], v[56:57]
	v_fma_f32 v58, s55, v52, -v54
	v_fma_f32 v59, s55, v53, -v55
	v_cvt_pk_bf16_f32 v60, v58, v59
	global_store_dword v10, v60, s[64:65]
	s_add_u32 s64, s64, 0x1000
	s_addc_u32 s65, s65, 0
	v_mov_b64_e32 v[50:51], v[54:55]
	s_add_i32 s61, s61, 1
	s_cmp_lt_u32 s61, 4
	s_cbranch_scc1 .Lpp_w2_blk
	s_branch .Lpp_next
.Lpp_w4:
	s_cmp_eq_u32 s60, 0
	s_cbranch_scc1 .Lpp_w4_zero
	s_sub_u32 s0, s62, 0xf000
	s_subb_u32 s1, s63, 0
	global_load_dword v79, v10, s[0:1]
	s_add_u32 s0, s0, 0x1000
	s_addc_u32 s1, s1, 0
	global_load_dword v80, v10, s[0:1]
	s_add_u32 s0, s0, 0x1000
	s_addc_u32 s1, s1, 0
	global_load_dword v81, v10, s[0:1]
	s_add_u32 s0, s0, 0x1000
	s_addc_u32 s1, s1, 0
	global_load_dword v82, v10, s[0:1]
	s_add_u32 s0, s0, 0x1000
	s_addc_u32 s1, s1, 0
	global_load_dword v83, v10, s[0:1]
	s_add_u32 s0, s0, 0x1000
	s_addc_u32 s1, s1, 0
	global_load_dword v84, v10, s[0:1]
	s_add_u32 s0, s0, 0x1000
	s_addc_u32 s1, s1, 0
	global_load_dword v85, v10, s[0:1]
	s_add_u32 s0, s0, 0x1000
	s_addc_u32 s1, s1, 0
	global_load_dword v86, v10, s[0:1]
	s_add_u32 s0, s0, 0x1000
	s_addc_u32 s1, s1, 0
	global_load_dword v87, v10, s[0:1]
	s_add_u32 s0, s0, 0x1000
	s_addc_u32 s1, s1, 0
	global_load_dword v88, v10, s[0:1]
	s_add_u32 s0, s0, 0x1000
	s_addc_u32 s1, s1, 0
	global_load_dword v89, v10, s[0:1]
	s_add_u32 s0, s0, 0x1000
	s_addc_u32 s1, s1, 0
	global_load_dword v90, v10, s[0:1]
	s_add_u32 s0, s0, 0x1000
	s_addc_u32 s1, s1, 0
	global_load_dword v91, v10, s[0:1]
	s_add_u32 s0, s0, 0x1000
	s_addc_u32 s1, s1, 0
	global_load_dword v92, v10, s[0:1]
	s_add_u32 s0, s0, 0x1000
	s_addc_u32 s1, s1, 0
	global_load_dword v93, v10, s[0:1]
	s_add_u32 s0, s0, 0x1000
	s_addc_u32 s1, s1, 0
	s_waitcnt vmcnt(0)
	v_mov_b64_e32 v[20:21], 0
	v_mov_b64_e32 v[52:53], 0
	v_lshlrev_b32_e32 v22, 16, v79
	v_and_b32_e32 v23, 0xffff0000, v79
	v_lshlrev_b32_e32 v24, 16, v80
	v_and_b32_e32 v25, 0xffff0000, v80
	v_lshlrev_b32_e32 v26, 16, v81
	v_and_b32_e32 v27, 0xffff0000, v81
	v_lshlrev_b32_e32 v28, 16, v82
	v_and_b32_e32 v29, 0xffff0000, v82
	v_lshlrev_b32_e32 v30, 16, v83
	v_and_b32_e32 v31, 0xffff0000, v83
	v_lshlrev_b32_e32 v32, 16, v84
	v_and_b32_e32 v33, 0xffff0000, v84
	v_lshlrev_b32_e32 v34, 16, v85
	v_and_b32_e32 v35, 0xffff0000, v85
	v_lshlrev_b32_e32 v36, 16, v86
	v_and_b32_e32 v37, 0xffff0000, v86
	v_lshlrev_b32_e32 v38, 16, v87
	v_and_b32_e32 v39, 0xffff0000, v87
	v_lshlrev_b32_e32 v40, 16, v88
	v_and_b32_e32 v41, 0xffff0000, v88
	v_lshlrev_b32_e32 v42, 16, v89
	v_and_b32_e32 v43, 0xffff0000, v89
	v_lshlrev_b32_e32 v44, 16, v90
	v_and_b32_e32 v45, 0xffff0000, v90
	v_lshlrev_b32_e32 v46, 16, v91
	v_and_b32_e32 v47, 0xffff0000, v91
	v_lshlrev_b32_e32 v48, 16, v92
	v_and_b32_e32 v49, 0xffff0000, v92
	v_lshlrev_b32_e32 v50, 16, v93
	v_and_b32_e32 v51, 0xffff0000, v93
	v_pk_add_f32 v[52:53], v[52:53], v[44:45]
	v_pk_add_f32 v[52:53], v[52:53], v[46:47]
	v_pk_add_f32 v[52:53], v[52:53], v[48:49]
	v_pk_add_f32 v[52:53], v[52:53], v[50:51]
	s_branch .Lpp_w4_go

; __device__ __forceinline__ unsigned cvtpk(float lo, float hi) { return pg8::cvt_pk_bf16(lo, hi); }
; __device__ __forceinline__ float bflo(unsigned u) { return __uint_as_float(u << 16); }
; __device__ __forceinline__ float bfhi(unsigned u) { return __uint_as_float(u & 0xffff0000u); }
; __device__ __forceinline__ void pool_pre_phase(const bf16_t* hn, bf16_t* yp, int gtid, int ngt) {
;     ...
;         for (int tb = 0; tb < 64; tb += 16) {
; #pragma unroll
;             for (int i = 0; i < 16; ++i) { const int t = tb + i; const unsigned v = *(const unsigned*)(p + (size_t)t * DM);
;                 const float n0 = bflo(v), n1 = bfhi(v);
;                 const float o0 = r0[(i + 16 - w) & 15], o1 = r1[(i + 16 - w) & 15];
;                 s0 += n0 - o0; s1 += n1 - o1; r0[i] = n0; r1[i] = n1;
;                 const int cnt = (tr0 + t + 1 < w) ? (tr0 + t + 1) : w; const float inv = 1.0f / (float)cnt;
;                 *(unsigned*)(yp + (row0 + t) * DM + col) = cvtpk(s0 * inv - n0, s1 * inv - n1); }
.Lpp_w4_blk:
	s_mov_b32 s40, 0x3e800000
	s_mov_b32 s41, 0x3e800000
	s_mov_b32 s42, 0x3e800000
	s_mov_b32 s43, 0x3e800000
	s_mov_b32 s44, 0x3e800000
	s_mov_b32 s45, 0x3e800000
	s_mov_b32 s46, 0x3e800000
	s_mov_b32 s47, 0x3e800000
	s_mov_b32 s48, 0x3e800000
	s_mov_b32 s49, 0x3e800000
	s_mov_b32 s50, 0x3e800000
	s_mov_b32 s51, 0x3e800000
	s_mov_b32 s52, 0x3e800000
	s_mov_b32 s53, 0x3e800000
	s_mov_b32 s54, 0x3e800000
	s_mov_b32 s55, 0x3e800000
	s_or_b32 s66, s60, s61
	s_cmp_lg_u32 s66, 0
	s_cbranch_scc1 .Lpp_w4_ld
	s_mov_b32 s40, 0x3f800000
	s_mov_b32 s41, 0x3f000000
	s_mov_b32 s42, 0x3eaaaaab
.Lpp_w4_ld:
	s_mov_b64 s[0:1], s[62:63]
	global_load_dword v62, v10, s[0:1]
	s_add_u32 s0, s0, 0x1000
	s_addc_u32 s1, s1, 0
	global_load_dword v63, v10, s[0:1]
	s_add_u32 s0, s0, 0x1000
	s_addc_u32 s1, s1, 0
	global_load_dword v64, v10, s[0:1]
	s_add_u32 s0, s0, 0x1000
	s_addc_u32 s1, s1, 0
	global_load_dword v65, v10, s[0:1]
	s_add_u32 s0, s0, 0x1000
	s_addc_u32 s1, s1, 0
	global_load_dword v66, v10, s[0:1]
	s_add_u32 s0, s0, 0x1000
	s_addc_u32 s1, s1, 0
	global_load_dword v67, v10, s[0:1]
	s_add_u32 s0, s0, 0x1000
	s_addc_u32 s1, s1, 0
	global_load_dword v68, v10, s[0:1]
	s_add_u32 s0, s0, 0x1000
	s_addc_u32 s1, s1, 0
	global_load_dword v69, v10, s[0:1]
	s_add_u32 s0, s0, 0x1000
	s_addc_u32 s1, s1, 0
	global_load_dword v70, v10, s[0:1]
	s_add_u32 s0, s0, 0x1000
	s_addc_u32 s1, s1, 0
	global_load_dword v71, v10, s[0:1]
	s_add_u32 s0, s0, 0x1000
	s_addc_u32 s1, s1, 0
	global_load_dword v72, v10, s[0:1]
	s_add_u32 s0, s0, 0x1000
	s_addc_u32 s1, s1, 0
	global_load_dword v73, v10, s[0:1]
	s_add_u32 s0, s0, 0x1000
	s_addc_u32 s1, s1, 0
	global_load_dword v74, v10, s[0:1]
	s_add_u32 s0, s0, 0x1000
	s_addc_u32 s1, s1, 0
	global_load_dword v75, v10, s[0:1]
	s_add_u32 s0, s0, 0x1000
	s_addc_u32 s1, s1, 0
	global_load_dword v76, v10, s[0:1]
	s_add_u32 s0, s0, 0x1000
	s_addc_u32 s1, s1, 0
	global_load_dword v77, v10, s[0:1]
	s_add_u32 s0, s0, 0x1000
	s_addc_u32 s1, s1, 0
	s_mov_b64 s[62:63], s[0:1]
	s_waitcnt vmcnt(15)
	v_lshlrev_b32_e32 v54, 16, v62
	v_and_b32_e32 v55, 0xffff0000, v62
	v_pk_add_f32 v[56:57], v[54:55], v[44:45] neg_lo:[0,1] neg_hi:[0,1]
	v_pk_add_f32 v[52:53], v[52:53], v[56:57]
	v_fma_f32 v58, s40, v52, -v54
	v_fma_f32 v59, s40, v53, -v55
	v_cvt_pk_bf16_f32 v60, v58, v59
	global_store_dword v10, v60, s[64:65]
	s_add_u32 s64, s64, 0x1000
	s_addc_u32 s65, s65, 0
	v_mov_b64_e32 v[20:21], v[54:55]
	s_waitcnt vmcnt(15)
	v_lshlrev_b32_e32 v54, 16, v63
	v_and_b32_e32 v55, 0xffff0000, v63
	v_pk_add_f32 v[56:57], v[54:55], v[46:47] neg_lo:[0,1] neg_hi:[0,1]
	v_pk_add_f32 v[52:53], v[52:53], v[56:57]
	v_fma_f32 v58, s41, v52, -v54
	v_fma_f32 v59, s41, v53, -v55
	v_cvt_pk_bf16_f32 v60, v58, v59
	global_store_dword v10, v60, s[64:65]
	s_add_u32 s64, s64, 0x1000
	s_addc_u32 s65, s65, 0
	v_mov_b64_e32 v[22:23], v[54:55]
	s_waitcnt vmcnt(15)
	v_lshlrev_b32_e32 v54, 16, v64
	v_and_b32_e32 v55, 0xffff0000, v64
	v_pk_add_f32 v[56:57], v[54:55], v[48:49] neg_lo:[0,1] neg_hi:[0,1]
	v_pk_add_f32 v[52:53], v[52:53], v[56:57]
	v_fma_f32 v58, s42, v52, -v54
	v_fma_f32 v59, s42, v53, -v55
	v_cvt_pk_bf16_f32 v60, v58, v59
	global_store_dword v10, v60, s[64:65]
	s_add_u32 s64, s64, 0x1000
	s_addc_u32 s65, s65, 0
	v_mov_b64_e32 v[24:25], v[54:55]
	s_waitcnt vmcnt(15)
	v_lshlrev_b32_e32 v54, 16, v65
	v_and_b32_e32 v55, 0xffff0000, v65
	v_pk_add_f32 v[56:57], v[54:55], v[50:51] neg_lo:[0,1] neg_hi:[0,1]
	v_pk_add_f32 v[52:53], v[52:53], v[56:57]
	v_fma_f32 v58, s43, v52, -v54
	v_fma_f32 v59, s43, v53, -v55
	v_cvt_pk_bf16_f32 v60, v58, v59
	global_store_dword v10, v60, s[64:65]
	s_add_u32 s64, s64, 0x1000
	s_addc_u32 s65, s65, 0
	v_mov_b64_e32 v[26:27], v[54:55]
	s_waitcnt vmcnt(15)
	v_lshlrev_b32_e32 v54, 16, v66
	v_and_b32_e32 v55, 0xffff0000, v66
	v_pk_add_f32 v[56:57], v[54:55], v[20:21] neg_lo:[0,1] neg_hi:[0,1]
	v_pk_add_f32 v[52:53], v[52:53], v[56:57]
	v_fma_f32 v58, s44, v52, -v54
	v_fma_f32 v59, s44, v53, -v55
	v_cvt_pk_bf16_f32 v60, v58, v59
	global_store_dword v10, v60, s[64:65]
	s_add_u32 s64, s64, 0x1000
	s_addc_u32 s65, s65, 0
	v_mov_b64_e32 v[28:29], v[54:55]
	s_waitcnt vmcnt(15)
	v_lshlrev_b32_e32 v54, 16, v67
	v_and_b32_e32 v55, 0xffff0000, v67
	v_pk_add_f32 v[56:57], v[54:55], v[22:23] neg_lo:[0,1] neg_hi:[0,1]
	v_pk_add_f32 v[52:53], v[52:53], v[56:57]
	v_fma_f32 v58, s45, v52, -v54
	v_fma_f32 v59, s45, v53, -v55
	v_cvt_pk_bf16_f32 v60, v58, v59
	global_store_dword v10, v60, s[64:65]
	s_add_u32 s64, s64, 0x1000
	s_addc_u32 s65, s65, 0
	v_mov_b64_e32 v[30:31], v[54:55]
	s_waitcnt vmcnt(15)
	v_lshlrev_b32_e32 v54, 16, v68
	v_and_b32_e32 v55, 0xffff0000, v68
	v_pk_add_f32 v[56:57], v[54:55], v[24:25] neg_lo:[0,1] neg_hi:[0,1]
	v_pk_add_f32 v[52:53], v[52:53], v[56:57]
	v_fma_f32 v58, s46, v52, -v54
	v_fma_f32 v59, s46, v53, -v55
	v_cvt_pk_bf16_f32 v60, v58, v59
	global_store_dword v10, v60, s[64:65]
	s_add_u32 s64, s64, 0x1000
	s_addc_u32 s65, s65, 0
	v_mov_b64_e32 v[32:33], v[54:55]
	s_waitcnt vmcnt(15)
	v_lshlrev_b32_e32 v54, 16, v69
	v_and_b32_e32 v55, 0xffff0000, v69
	v_pk_add_f32 v[56:57], v[54:55], v[26:27] neg_lo:[0,1] neg_hi:[0,1]
	v_pk_add_f32 v[52:53], v[52:53], v[56:57]
	v_fma_f32 v58, s47, v52, -v54
	v_fma_f32 v59, s47, v53, -v55
	v_cvt_pk_bf16_f32 v60, v58, v59
	global_store_dword v10, v60, s[64:65]
	s_add_u32 s64, s64, 0x1000
	s_addc_u32 s65, s65, 0
	v_mov_b64_e32 v[34:35], v[54:55]
	s_waitcnt vmcnt(15)
	v_lshlrev_b32_e32 v54, 16, v70
	v_and_b32_e32 v55, 0xffff0000, v70
	v_pk_add_f32 v[56:57], v[54:55], v[28:29] neg_lo:[0,1] neg_hi:[0,1]
	v_pk_add_f32 v[52:53], v[52:53], v[56:57]
	v_fma_f32 v58, s48, v52, -v54
	v_fma_f32 v59, s48, v53, -v55
	v_cvt_pk_bf16_f32 v60, v58, v59
	global_store_dword v10, v60, s[64:65]
	s_add_u32 s64, s64, 0x1000
	s_addc_u32 s65, s65, 0
	v_mov_b64_e32 v[36:37], v[54:55]
	s_waitcnt vmcnt(15)
; __device__ __forceinline__ unsigned cvtpk(float lo, float hi) { return pg8::cvt_pk_bf16(lo, hi); }
; __device__ __forceinline__ float bflo(unsigned u) { return __uint_as_float(u << 16); }
; __device__ __forceinline__ float bfhi(unsigned u) { return __uint_as_float(u & 0xffff0000u); }
; __device__ __forceinline__ void pool_pre_phase(const bf16_t* hn, bf16_t* yp, int gtid, int ngt) {
;     ...
;         if (tr0 > 0) {
; #pragma unroll
;             for (int i = 1; i < 16; ++i) { const unsigned v = *(const unsigned*)(p - (size_t)(16 - i) * DM); r0[i] = bflo(v); r1[i] = bfhi(v);
;                 if (16 - i <= w) { s0 += r0[i]; s1 += r1[i]; } }
;         }
;         for (int tb = 0; tb < 64; tb += 16) {
; #pragma unroll
;             for (int i = 0; i < 16; ++i) { const int t = tb + i; const unsigned v = *(const unsigned*)(p + (size_t)t * DM);
;                 const float n0 = bflo(v), n1 = bfhi(v);
;                 const float o0 = r0[(i + 16 - w) & 15], o1 = r1[(i + 16 - w) & 15];
;                 s0 += n0 - o0; s1 += n1 - o1; r0[i] = n0; r1[i] = n1;
;                 const int cnt = (tr0 + t + 1 < w) ? (tr0 + t + 1) : w; const float inv = 1.0f / (float)cnt;
;                 *(unsigned*)(yp + (row0 + t) * DM + col) = cvtpk(s0 * inv - n0, s1 * inv - n1); }
	v_lshlrev_b32_e32 v54, 16, v71
	v_and_b32_e32 v55, 0xffff0000, v71
	v_pk_add_f32 v[56:57], v[54:55], v[30:31] neg_lo:[0,1] neg_hi:[0,1]
	v_pk_add_f32 v[52:53], v[52:53], v[56:57]
	v_fma_f32 v58, s49, v52, -v54
	v_fma_f32 v59, s49, v53, -v55
	v_cvt_pk_bf16_f32 v60, v58, v59
	global_store_dword v10, v60, s[64:65]
	s_add_u32 s64, s64, 0x1000
	s_addc_u32 s65, s65, 0
	v_mov_b64_e32 v[38:39], v[54:55]
	s_waitcnt vmcnt(15)
	v_lshlrev_b32_e32 v54, 16, v72
	v_and_b32_e32 v55, 0xffff0000, v72
	v_pk_add_f32 v[56:57], v[54:55], v[32:33] neg_lo:[0,1] neg_hi:[0,1]
	v_pk_add_f32 v[52:53], v[52:53], v[56:57]
	v_fma_f32 v58, s50, v52, -v54
	v_fma_f32 v59, s50, v53, -v55
	v_cvt_pk_bf16_f32 v60, v58, v59
	global_store_dword v10, v60, s[64:65]
	s_add_u32 s64, s64, 0x1000
	s_addc_u32 s65, s65, 0
	v_mov_b64_e32 v[40:41], v[54:55]
	s_waitcnt vmcnt(15)
	v_lshlrev_b32_e32 v54, 16, v73
	v_and_b32_e32 v55, 0xffff0000, v73
	v_pk_add_f32 v[56:57], v[54:55], v[34:35] neg_lo:[0,1] neg_hi:[0,1]
	v_pk_add_f32 v[52:53], v[52:53], v[56:57]
	v_fma_f32 v58, s51, v52, -v54
	v_fma_f32 v59, s51, v53, -v55
	v_cvt_pk_bf16_f32 v60, v58, v59
	global_store_dword v10, v60, s[64:65]
	s_add_u32 s64, s64, 0x1000
	s_addc_u32 s65, s65, 0
	v_mov_b64_e32 v[42:43], v[54:55]
	s_waitcnt vmcnt(15)
	v_lshlrev_b32_e32 v54, 16, v74
	v_and_b32_e32 v55, 0xffff0000, v74
	v_pk_add_f32 v[56:57], v[54:55], v[36:37] neg_lo:[0,1] neg_hi:[0,1]
	v_pk_add_f32 v[52:53], v[52:53], v[56:57]
	v_fma_f32 v58, s52, v52, -v54
	v_fma_f32 v59, s52, v53, -v55
	v_cvt_pk_bf16_f32 v60, v58, v59
	global_store_dword v10, v60, s[64:65]
	s_add_u32 s64, s64, 0x1000
	s_addc_u32 s65, s65, 0
	v_mov_b64_e32 v[44:45], v[54:55]
	s_waitcnt vmcnt(15)
	v_lshlrev_b32_e32 v54, 16, v75
	v_and_b32_e32 v55, 0xffff0000, v75
	v_pk_add_f32 v[56:57], v[54:55], v[38:39] neg_lo:[0,1] neg_hi:[0,1]
	v_pk_add_f32 v[52:53], v[52:53], v[56:57]
	v_fma_f32 v58, s53, v52, -v54
	v_fma_f32 v59, s53, v53, -v55
	v_cvt_pk_bf16_f32 v60, v58, v59
	global_store_dword v10, v60, s[64:65]
	s_add_u32 s64, s64, 0x1000
	s_addc_u32 s65, s65, 0
	v_mov_b64_e32 v[46:47], v[54:55]
	s_waitcnt vmcnt(15)
	v_lshlrev_b32_e32 v54, 16, v76
	v_and_b32_e32 v55, 0xffff0000, v76
	v_pk_add_f32 v[56:57], v[54:55], v[40:41] neg_lo:[0,1] neg_hi:[0,1]
	v_pk_add_f32 v[52:53], v[52:53], v[56:57]
	v_fma_f32 v58, s54, v52, -v54
	v_fma_f32 v59, s54, v53, -v55
	v_cvt_pk_bf16_f32 v60, v58, v59
	global_store_dword v10, v60, s[64:65]
	s_add_u32 s64, s64, 0x1000
	s_addc_u32 s65, s65, 0
	v_mov_b64_e32 v[48:49], v[54:55]
	s_waitcnt vmcnt(15)
	v_lshlrev_b32_e32 v54, 16, v77
	v_and_b32_e32 v55, 0xffff0000, v77
	v_pk_add_f32 v[56:57], v[54:55], v[42:43] neg_lo:[0,1] neg_hi:[0,1]
	v_pk_add_f32 v[52:53], v[52:53], v[56:57]
	v_fma_f32 v58, s55, v52, -v54
	v_fma_f32 v59, s55, v53, -v55
	v_cvt_pk_bf16_f32 v60, v58, v59
	global_store_dword v10, v60, s[64:65]
	s_add_u32 s64, s64, 0x1000
	s_addc_u32 s65, s65, 0
	v_mov_b64_e32 v[50:51], v[54:55]
	s_add_i32 s61, s61, 1
	s_cmp_lt_u32 s61, 4
	s_cbranch_scc1 .Lpp_w4_blk
	s_branch .Lpp_next
.Lpp_w8:
	s_cmp_eq_u32 s60, 0
	s_cbranch_scc1 .Lpp_w8_zero
	s_sub_u32 s0, s62, 0xf000
	s_subb_u32 s1, s63, 0
	global_load_dword v79, v10, s[0:1]
	s_add_u32 s0, s0, 0x1000
	s_addc_u32 s1, s1, 0
	global_load_dword v80, v10, s[0:1]
	s_add_u32 s0, s0, 0x1000
	s_addc_u32 s1, s1, 0
	global_load_dword v81, v10, s[0:1]
	s_add_u32 s0, s0, 0x1000
	s_addc_u32 s1, s1, 0
	global_load_dword v82, v10, s[0:1]
	s_add_u32 s0, s0, 0x1000
	s_addc_u32 s1, s1, 0
	global_load_dword v83, v10, s[0:1]
	s_add_u32 s0, s0, 0x1000
	s_addc_u32 s1, s1, 0
	global_load_dword v84, v10, s[0:1]
	s_add_u32 s0, s0, 0x1000
	s_addc_u32 s1, s1, 0
	global_load_dword v85, v10, s[0:1]
	s_add_u32 s0, s0, 0x1000
	s_addc_u32 s1, s1, 0
	global_load_dword v86, v10, s[0:1]
	s_add_u32 s0, s0, 0x1000
	s_addc_u32 s1, s1, 0
	global_load_dword v87, v10, s[0:1]
	s_add_u32 s0, s0, 0x1000
	s_addc_u32 s1, s1, 0
	global_load_dword v88, v10, s[0:1]
	s_add_u32 s0, s0, 0x1000
	s_addc_u32 s1, s1, 0
	global_load_dword v89, v10, s[0:1]
	s_add_u32 s0, s0, 0x1000
	s_addc_u32 s1, s1, 0
	global_load_dword v90, v10, s[0:1]
	s_add_u32 s0, s0, 0x1000
	s_addc_u32 s1, s1, 0
	global_load_dword v91, v10, s[0:1]
	s_add_u32 s0, s0, 0x1000
	s_addc_u32 s1, s1, 0
	global_load_dword v92, v10, s[0:1]
	s_add_u32 s0, s0, 0x1000
	s_addc_u32 s1, s1, 0
	global_load_dword v93, v10, s[0:1]
	s_add_u32 s0, s0, 0x1000
	s_addc_u32 s1, s1, 0
	s_waitcnt vmcnt(0)
	v_mov_b64_e32 v[20:21], 0
	v_mov_b64_e32 v[52:53], 0
	v_lshlrev_b32_e32 v22, 16, v79
	v_and_b32_e32 v23, 0xffff0000, v79
	v_lshlrev_b32_e32 v24, 16, v80
	v_and_b32_e32 v25, 0xffff0000, v80
	v_lshlrev_b32_e32 v26, 16, v81
	v_and_b32_e32 v27, 0xffff0000, v81
	v_lshlrev_b32_e32 v28, 16, v82
	v_and_b32_e32 v29, 0xffff0000, v82
	v_lshlrev_b32_e32 v30, 16, v83
	v_and_b32_e32 v31, 0xffff0000, v83
	v_lshlrev_b32_e32 v32, 16, v84
	v_and_b32_e32 v33, 0xffff0000, v84
	v_lshlrev_b32_e32 v34, 16, v85
	v_and_b32_e32 v35, 0xffff0000, v85
	v_lshlrev_b32_e32 v36, 16, v86
	v_and_b32_e32 v37, 0xffff0000, v86
	v_lshlrev_b32_e32 v38, 16, v87
	v_and_b32_e32 v39, 0xffff0000, v87
	v_lshlrev_b32_e32 v40, 16, v88
	v_and_b32_e32 v41, 0xffff0000, v88
	v_lshlrev_b32_e32 v42, 16, v89
	v_and_b32_e32 v43, 0xffff0000, v89
	v_lshlrev_b32_e32 v44, 16, v90
	v_and_b32_e32 v45, 0xffff0000, v90
	v_lshlrev_b32_e32 v46, 16, v91
	v_and_b32_e32 v47, 0xffff0000, v91
	v_lshlrev_b32_e32 v48, 16, v92
	v_and_b32_e32 v49, 0xffff0000, v92
	v_lshlrev_b32_e32 v50, 16, v93
	v_and_b32_e32 v51, 0xffff0000, v93
	v_pk_add_f32 v[52:53], v[52:53], v[36:37]
	v_pk_add_f32 v[52:53], v[52:53], v[38:39]
	v_pk_add_f32 v[52:53], v[52:53], v[40:41]
	v_pk_add_f32 v[52:53], v[52:53], v[42:43]
	v_pk_add_f32 v[52:53], v[52:53], v[44:45]
	v_pk_add_f32 v[52:53], v[52:53], v[46:47]
	v_pk_add_f32 v[52:53], v[52:53], v[48:49]
	v_pk_add_f32 v[52:53], v[52:53], v[50:51]
	s_branch .Lpp_w8_go

; __device__ __forceinline__ unsigned cvtpk(float lo, float hi) { return pg8::cvt_pk_bf16(lo, hi); }
; __device__ __forceinline__ float bflo(unsigned u) { return __uint_as_float(u << 16); }
; __device__ __forceinline__ float bfhi(unsigned u) { return __uint_as_float(u & 0xffff0000u); }
; __device__ __forceinline__ void pool_pre_phase(const bf16_t* hn, bf16_t* yp, int gtid, int ngt) {
;     ...
;         for (int tb = 0; tb < 64; tb += 16) {
; #pragma unroll
;             for (int i = 0; i < 16; ++i) { const int t = tb + i; const unsigned v = *(const unsigned*)(p + (size_t)t * DM);
;                 const float n0 = bflo(v), n1 = bfhi(v);
;                 const float o0 = r0[(i + 16 - w) & 15], o1 = r1[(i + 16 - w) & 15];
;                 s0 += n0 - o0; s1 += n1 - o1; r0[i] = n0; r1[i] = n1;
;                 const int cnt = (tr0 + t + 1 < w) ? (tr0 + t + 1) : w; const float inv = 1.0f / (float)cnt;
;                 *(unsigned*)(yp + (row0 + t) * DM + col) = cvtpk(s0 * inv - n0, s1 * inv - n1); }
.Lpp_w8_blk:
	s_mov_b32 s40, 0x3e000000
	s_mov_b32 s41, 0x3e000000
	s_mov_b32 s42, 0x3e000000
	s_mov_b32 s43, 0x3e000000
	s_mov_b32 s44, 0x3e000000
	s_mov_b32 s45, 0x3e000000
	s_mov_b32 s46, 0x3e000000
	s_mov_b32 s47, 0x3e000000
	s_mov_b32 s48, 0x3e000000
	s_mov_b32 s49, 0x3e000000
	s_mov_b32 s50, 0x3e000000
	s_mov_b32 s51, 0x3e000000
	s_mov_b32 s52, 0x3e000000
	s_mov_b32 s53, 0x3e000000
	s_mov_b32 s54, 0x3e000000
	s_mov_b32 s55, 0x3e000000
	s_or_b32 s66, s60, s61
	s_cmp_lg_u32 s66, 0
	s_cbranch_scc1 .Lpp_w8_ld
	s_mov_b32 s40, 0x3f800000
	s_mov_b32 s41, 0x3f000000
	s_mov_b32 s42, 0x3eaaaaab
	s_mov_b32 s43, 0x3e800000
	s_mov_b32 s44, 0x3e4ccccd
	s_mov_b32 s45, 0x3e2aaaab
	s_mov_b32 s46, 0x3e124925
.Lpp_w8_ld:
	s_mov_b64 s[0:1], s[62:63]
	global_load_dword v62, v10, s[0:1]
	s_add_u32 s0, s0, 0x1000
	s_addc_u32 s1, s1, 0
	global_load_dword v63, v10, s[0:1]
	s_add_u32 s0, s0, 0x1000
	s_addc_u32 s1, s1, 0
	global_load_dword v64, v10, s[0:1]
	s_add_u32 s0, s0, 0x1000
	s_addc_u32 s1, s1, 0
	global_load_dword v65, v10, s[0:1]
	s_add_u32 s0, s0, 0x1000
	s_addc_u32 s1, s1, 0
	global_load_dword v66, v10, s[0:1]
	s_add_u32 s0, s0, 0x1000
	s_addc_u32 s1, s1, 0
	global_load_dword v67, v10, s[0:1]
	s_add_u32 s0, s0, 0x1000
	s_addc_u32 s1, s1, 0
	global_load_dword v68, v10, s[0:1]
	s_add_u32 s0, s0, 0x1000
	s_addc_u32 s1, s1, 0
	global_load_dword v69, v10, s[0:1]
	s_add_u32 s0, s0, 0x1000
	s_addc_u32 s1, s1, 0
	global_load_dword v70, v10, s[0:1]
	s_add_u32 s0, s0, 0x1000
	s_addc_u32 s1, s1, 0
	global_load_dword v71, v10, s[0:1]
	s_add_u32 s0, s0, 0x1000
	s_addc_u32 s1, s1, 0
	global_load_dword v72, v10, s[0:1]
	s_add_u32 s0, s0, 0x1000
	s_addc_u32 s1, s1, 0
	global_load_dword v73, v10, s[0:1]
	s_add_u32 s0, s0, 0x1000
	s_addc_u32 s1, s1, 0
	global_load_dword v74, v10, s[0:1]
	s_add_u32 s0, s0, 0x1000
	s_addc_u32 s1, s1, 0
	global_load_dword v75, v10, s[0:1]
	s_add_u32 s0, s0, 0x1000
	s_addc_u32 s1, s1, 0
	global_load_dword v76, v10, s[0:1]
	s_add_u32 s0, s0, 0x1000
	s_addc_u32 s1, s1, 0
	global_load_dword v77, v10, s[0:1]
	s_add_u32 s0, s0, 0x1000
	s_addc_u32 s1, s1, 0
	s_mov_b64 s[62:63], s[0:1]
	s_waitcnt vmcnt(15)
	v_lshlrev_b32_e32 v54, 16, v62
	v_and_b32_e32 v55, 0xffff0000, v62
	v_pk_add_f32 v[56:57], v[54:55], v[36:37] neg_lo:[0,1] neg_hi:[0,1]
	v_pk_add_f32 v[52:53], v[52:53], v[56:57]
	v_fma_f32 v58, s40, v52, -v54
	v_fma_f32 v59, s40, v53, -v55
	v_cvt_pk_bf16_f32 v60, v58, v59
	global_store_dword v10, v60, s[64:65]
	s_add_u32 s64, s64, 0x1000
	s_addc_u32 s65, s65, 0
	v_mov_b64_e32 v[20:21], v[54:55]
	s_waitcnt vmcnt(15)
	v_lshlrev_b32_e32 v54, 16, v63
	v_and_b32_e32 v55, 0xffff0000, v63
	v_pk_add_f32 v[56:57], v[54:55], v[38:39] neg_lo:[0,1] neg_hi:[0,1]
	v_pk_add_f32 v[52:53], v[52:53], v[56:57]
	v_fma_f32 v58, s41, v52, -v54
	v_fma_f32 v59, s41, v53, -v55
	v_cvt_pk_bf16_f32 v60, v58, v59
	global_store_dword v10, v60, s[64:65]
	s_add_u32 s64, s64, 0x1000
	s_addc_u32 s65, s65, 0
	v_mov_b64_e32 v[22:23], v[54:55]
	s_waitcnt vmcnt(15)
	v_lshlrev_b32_e32 v54, 16, v64
	v_and_b32_e32 v55, 0xffff0000, v64
	v_pk_add_f32 v[56:57], v[54:55], v[40:41] neg_lo:[0,1] neg_hi:[0,1]
	v_pk_add_f32 v[52:53], v[52:53], v[56:57]
	v_fma_f32 v58, s42, v52, -v54
	v_fma_f32 v59, s42, v53, -v55
	v_cvt_pk_bf16_f32 v60, v58, v59
	global_store_dword v10, v60, s[64:65]
	s_add_u32 s64, s64, 0x1000
	s_addc_u32 s65, s65, 0
	v_mov_b64_e32 v[24:25], v[54:55]
	s_waitcnt vmcnt(15)
	v_lshlrev_b32_e32 v54, 16, v65
	v_and_b32_e32 v55, 0xffff0000, v65
	v_pk_add_f32 v[56:57], v[54:55], v[42:43] neg_lo:[0,1] neg_hi:[0,1]
	v_pk_add_f32 v[52:53], v[52:53], v[56:57]
	v_fma_f32 v58, s43, v52, -v54
	v_fma_f32 v59, s43, v53, -v55
	v_cvt_pk_bf16_f32 v60, v58, v59
	global_store_dword v10, v60, s[64:65]
	s_add_u32 s64, s64, 0x1000
	s_addc_u32 s65, s65, 0
	v_mov_b64_e32 v[26:27], v[54:55]
	s_waitcnt vmcnt(15)
	v_lshlrev_b32_e32 v54, 16, v66
	v_and_b32_e32 v55, 0xffff0000, v66
	v_pk_add_f32 v[56:57], v[54:55], v[44:45] neg_lo:[0,1] neg_hi:[0,1]
	v_pk_add_f32 v[52:53], v[52:53], v[56:57]
	v_fma_f32 v58, s44, v52, -v54
	v_fma_f32 v59, s44, v53, -v55
	v_cvt_pk_bf16_f32 v60, v58, v59
	global_store_dword v10, v60, s[64:65]
	s_add_u32 s64, s64, 0x1000
	s_addc_u32 s65, s65, 0
	v_mov_b64_e32 v[28:29], v[54:55]
	s_waitcnt vmcnt(15)
	v_lshlrev_b32_e32 v54, 16, v67
	v_and_b32_e32 v55, 0xffff0000, v67
	v_pk_add_f32 v[56:57], v[54:55], v[46:47] neg_lo:[0,1] neg_hi:[0,1]
	v_pk_add_f32 v[52:53], v[52:53], v[56:57]
	v_fma_f32 v58, s45, v52, -v54
	v_fma_f32 v59, s45, v53, -v55
	v_cvt_pk_bf16_f32 v60, v58, v59
	global_store_dword v10, v60, s[64:65]
	s_add_u32 s64, s64, 0x1000
	s_addc_u32 s65, s65, 0
	v_mov_b64_e32 v[30:31], v[54:55]
	s_waitcnt vmcnt(15)
	v_lshlrev_b32_e32 v54, 16, v68
	v_and_b32_e32 v55, 0xffff0000, v68
	v_pk_add_f32 v[56:57], v[54:55], v[48:49] neg_lo:[0,1] neg_hi:[0,1]
	v_pk_add_f32 v[52:53], v[52:53], v[56:57]
	v_fma_f32 v58, s46, v52, -v54
	v_fma_f32 v59, s46, v53, -v55
	v_cvt_pk_bf16_f32 v60, v58, v59
	global_store_dword v10, v60, s[64:65]
	s_add_u32 s64, s64, 0x1000
	s_addc_u32 s65, s65, 0
	v_mov_b64_e32 v[32:33], v[54:55]
	s_waitcnt vmcnt(15)
	v_lshlrev_b32_e32 v54, 16, v69
	v_and_b32_e32 v55, 0xffff0000, v69
	v_pk_add_f32 v[56:57], v[54:55], v[50:51] neg_lo:[0,1] neg_hi:[0,1]
	v_pk_add_f32 v[52:53], v[52:53], v[56:57]
	v_fma_f32 v58, s47, v52, -v54
	v_fma_f32 v59, s47, v53, -v55
	v_cvt_pk_bf16_f32 v60, v58, v59
	global_store_dword v10, v60, s[64:65]
	s_add_u32 s64, s64, 0x1000
	s_addc_u32 s65, s65, 0
	v_mov_b64_e32 v[34:35], v[54:55]
	s_waitcnt vmcnt(15)
; __device__ __forceinline__ unsigned cvtpk(float lo, float hi) { return pg8::cvt_pk_bf16(lo, hi); }
; __device__ __forceinline__ float bflo(unsigned u) { return __uint_as_float(u << 16); }
; __device__ __forceinline__ float bfhi(unsigned u) { return __uint_as_float(u & 0xffff0000u); }
; __device__ __forceinline__ void pool_pre_phase(const bf16_t* hn, bf16_t* yp, int gtid, int ngt) {
;     ...
;         if (tr0 > 0) {
; #pragma unroll
;             for (int i = 1; i < 16; ++i) { const unsigned v = *(const unsigned*)(p - (size_t)(16 - i) * DM); r0[i] = bflo(v); r1[i] = bfhi(v);
;                 if (16 - i <= w) { s0 += r0[i]; s1 += r1[i]; } }
;         }
;         for (int tb = 0; tb < 64; tb += 16) {
; #pragma unroll
;             for (int i = 0; i < 16; ++i) { const int t = tb + i; const unsigned v = *(const unsigned*)(p + (size_t)t * DM);
;                 const float n0 = bflo(v), n1 = bfhi(v);
;                 const float o0 = r0[(i + 16 - w) & 15], o1 = r1[(i + 16 - w) & 15];
;                 s0 += n0 - o0; s1 += n1 - o1; r0[i] = n0; r1[i] = n1;
;                 const int cnt = (tr0 + t + 1 < w) ? (tr0 + t + 1) : w; const float inv = 1.0f / (float)cnt;
;                 *(unsigned*)(yp + (row0 + t) * DM + col) = cvtpk(s0 * inv - n0, s1 * inv - n1); }
	v_lshlrev_b32_e32 v54, 16, v70
	v_and_b32_e32 v55, 0xffff0000, v70
	v_pk_add_f32 v[56:57], v[54:55], v[20:21] neg_lo:[0,1] neg_hi:[0,1]
	v_pk_add_f32 v[52:53], v[52:53], v[56:57]
	v_fma_f32 v58, s48, v52, -v54
	v_fma_f32 v59, s48, v53, -v55
	v_cvt_pk_bf16_f32 v60, v58, v59
	global_store_dword v10, v60, s[64:65]
	s_add_u32 s64, s64, 0x1000
	s_addc_u32 s65, s65, 0
	v_mov_b64_e32 v[36:37], v[54:55]
	s_waitcnt vmcnt(15)
	v_lshlrev_b32_e32 v54, 16, v71
	v_and_b32_e32 v55, 0xffff0000, v71
	v_pk_add_f32 v[56:57], v[54:55], v[22:23] neg_lo:[0,1] neg_hi:[0,1]
	v_pk_add_f32 v[52:53], v[52:53], v[56:57]
	v_fma_f32 v58, s49, v52, -v54
	v_fma_f32 v59, s49, v53, -v55
	v_cvt_pk_bf16_f32 v60, v58, v59
	global_store_dword v10, v60, s[64:65]
	s_add_u32 s64, s64, 0x1000
	s_addc_u32 s65, s65, 0
	v_mov_b64_e32 v[38:39], v[54:55]
	s_waitcnt vmcnt(15)
	v_lshlrev_b32_e32 v54, 16, v72
	v_and_b32_e32 v55, 0xffff0000, v72
	v_pk_add_f32 v[56:57], v[54:55], v[24:25] neg_lo:[0,1] neg_hi:[0,1]
	v_pk_add_f32 v[52:53], v[52:53], v[56:57]
	v_fma_f32 v58, s50, v52, -v54
	v_fma_f32 v59, s50, v53, -v55
	v_cvt_pk_bf16_f32 v60, v58, v59
	global_store_dword v10, v60, s[64:65]
	s_add_u32 s64, s64, 0x1000
	s_addc_u32 s65, s65, 0
	v_mov_b64_e32 v[40:41], v[54:55]
	s_waitcnt vmcnt(15)
	v_lshlrev_b32_e32 v54, 16, v73
	v_and_b32_e32 v55, 0xffff0000, v73
	v_pk_add_f32 v[56:57], v[54:55], v[26:27] neg_lo:[0,1] neg_hi:[0,1]
	v_pk_add_f32 v[52:53], v[52:53], v[56:57]
	v_fma_f32 v58, s51, v52, -v54
	v_fma_f32 v59, s51, v53, -v55
	v_cvt_pk_bf16_f32 v60, v58, v59
	global_store_dword v10, v60, s[64:65]
	s_add_u32 s64, s64, 0x1000
	s_addc_u32 s65, s65, 0
	v_mov_b64_e32 v[42:43], v[54:55]
	s_waitcnt vmcnt(15)
	v_lshlrev_b32_e32 v54, 16, v74
	v_and_b32_e32 v55, 0xffff0000, v74
	v_pk_add_f32 v[56:57], v[54:55], v[28:29] neg_lo:[0,1] neg_hi:[0,1]
	v_pk_add_f32 v[52:53], v[52:53], v[56:57]
	v_fma_f32 v58, s52, v52, -v54
	v_fma_f32 v59, s52, v53, -v55
	v_cvt_pk_bf16_f32 v60, v58, v59
	global_store_dword v10, v60, s[64:65]
	s_add_u32 s64, s64, 0x1000
	s_addc_u32 s65, s65, 0
	v_mov_b64_e32 v[44:45], v[54:55]
	s_waitcnt vmcnt(15)
	v_lshlrev_b32_e32 v54, 16, v75
	v_and_b32_e32 v55, 0xffff0000, v75
	v_pk_add_f32 v[56:57], v[54:55], v[30:31] neg_lo:[0,1] neg_hi:[0,1]
	v_pk_add_f32 v[52:53], v[52:53], v[56:57]
	v_fma_f32 v58, s53, v52, -v54
	v_fma_f32 v59, s53, v53, -v55
	v_cvt_pk_bf16_f32 v60, v58, v59
	global_store_dword v10, v60, s[64:65]
	s_add_u32 s64, s64, 0x1000
	s_addc_u32 s65, s65, 0
	v_mov_b64_e32 v[46:47], v[54:55]
	s_waitcnt vmcnt(15)
	v_lshlrev_b32_e32 v54, 16, v76
	v_and_b32_e32 v55, 0xffff0000, v76
	v_pk_add_f32 v[56:57], v[54:55], v[32:33] neg_lo:[0,1] neg_hi:[0,1]
	v_pk_add_f32 v[52:53], v[52:53], v[56:57]
	v_fma_f32 v58, s54, v52, -v54
	v_fma_f32 v59, s54, v53, -v55
	v_cvt_pk_bf16_f32 v60, v58, v59
	global_store_dword v10, v60, s[64:65]
	s_add_u32 s64, s64, 0x1000
	s_addc_u32 s65, s65, 0
	v_mov_b64_e32 v[48:49], v[54:55]
	s_waitcnt vmcnt(15)
	v_lshlrev_b32_e32 v54, 16, v77
	v_and_b32_e32 v55, 0xffff0000, v77
	v_pk_add_f32 v[56:57], v[54:55], v[34:35] neg_lo:[0,1] neg_hi:[0,1]
	v_pk_add_f32 v[52:53], v[52:53], v[56:57]
	v_fma_f32 v58, s55, v52, -v54
	v_fma_f32 v59, s55, v53, -v55
	v_cvt_pk_bf16_f32 v60, v58, v59
	global_store_dword v10, v60, s[64:65]
	s_add_u32 s64, s64, 0x1000
	s_addc_u32 s65, s65, 0
	v_mov_b64_e32 v[50:51], v[54:55]
	s_add_i32 s61, s61, 1
	s_cmp_lt_u32 s61, 4
	s_cbranch_scc1 .Lpp_w8_blk
	s_branch .Lpp_next
.Lpp_w16:
	s_cmp_eq_u32 s60, 0
	s_cbranch_scc1 .Lpp_w16_zero
	s_sub_u32 s0, s62, 0xf000
	s_subb_u32 s1, s63, 0
	global_load_dword v79, v10, s[0:1]
	s_add_u32 s0, s0, 0x1000
	s_addc_u32 s1, s1, 0
	global_load_dword v80, v10, s[0:1]
	s_add_u32 s0, s0, 0x1000
	s_addc_u32 s1, s1, 0
	global_load_dword v81, v10, s[0:1]
	s_add_u32 s0, s0, 0x1000
	s_addc_u32 s1, s1, 0
	global_load_dword v82, v10, s[0:1]
	s_add_u32 s0, s0, 0x1000
	s_addc_u32 s1, s1, 0
	global_load_dword v83, v10, s[0:1]
	s_add_u32 s0, s0, 0x1000
	s_addc_u32 s1, s1, 0
	global_load_dword v84, v10, s[0:1]
	s_add_u32 s0, s0, 0x1000
	s_addc_u32 s1, s1, 0
	global_load_dword v85, v10, s[0:1]
	s_add_u32 s0, s0, 0x1000
	s_addc_u32 s1, s1, 0
	global_load_dword v86, v10, s[0:1]
	s_add_u32 s0, s0, 0x1000
	s_addc_u32 s1, s1, 0
	global_load_dword v87, v10, s[0:1]
	s_add_u32 s0, s0, 0x1000
	s_addc_u32 s1, s1, 0
	global_load_dword v88, v10, s[0:1]
	s_add_u32 s0, s0, 0x1000
	s_addc_u32 s1, s1, 0
	global_load_dword v89, v10, s[0:1]
	s_add_u32 s0, s0, 0x1000
	s_addc_u32 s1, s1, 0
	global_load_dword v90, v10, s[0:1]
	s_add_u32 s0, s0, 0x1000
	s_addc_u32 s1, s1, 0
	global_load_dword v91, v10, s[0:1]
	s_add_u32 s0, s0, 0x1000
	s_addc_u32 s1, s1, 0
	global_load_dword v92, v10, s[0:1]
	s_add_u32 s0, s0, 0x1000
	s_addc_u32 s1, s1, 0
	global_load_dword v93, v10, s[0:1]
	s_add_u32 s0, s0, 0x1000
	s_addc_u32 s1, s1, 0
	s_waitcnt vmcnt(0)
	v_mov_b64_e32 v[20:21], 0
	v_mov_b64_e32 v[52:53], 0
	v_lshlrev_b32_e32 v22, 16, v79
	v_and_b32_e32 v23, 0xffff0000, v79
	v_lshlrev_b32_e32 v24, 16, v80
	v_and_b32_e32 v25, 0xffff0000, v80
	v_lshlrev_b32_e32 v26, 16, v81
	v_and_b32_e32 v27, 0xffff0000, v81
	v_lshlrev_b32_e32 v28, 16, v82
	v_and_b32_e32 v29, 0xffff0000, v82
	v_lshlrev_b32_e32 v30, 16, v83
	v_and_b32_e32 v31, 0xffff0000, v83
	v_lshlrev_b32_e32 v32, 16, v84
	v_and_b32_e32 v33, 0xffff0000, v84
	v_lshlrev_b32_e32 v34, 16, v85
	v_and_b32_e32 v35, 0xffff0000, v85
	v_lshlrev_b32_e32 v36, 16, v86
	v_and_b32_e32 v37, 0xffff0000, v86
	v_lshlrev_b32_e32 v38, 16, v87
	v_and_b32_e32 v39, 0xffff0000, v87
	v_lshlrev_b32_e32 v40, 16, v88
	v_and_b32_e32 v41, 0xffff0000, v88
	v_lshlrev_b32_e32 v42, 16, v89
	v_and_b32_e32 v43, 0xffff0000, v89
	v_lshlrev_b32_e32 v44, 16, v90
	v_and_b32_e32 v45, 0xffff0000, v90
	v_lshlrev_b32_e32 v46, 16, v91
	v_and_b32_e32 v47, 0xffff0000, v91
	v_lshlrev_b32_e32 v48, 16, v92
	v_and_b32_e32 v49, 0xffff0000, v92
	v_lshlrev_b32_e32 v50, 16, v93
	v_and_b32_e32 v51, 0xffff0000, v93
	v_pk_add_f32 v[52:53], v[52:53], v[22:23]
	v_pk_add_f32 v[52:53], v[52:53], v[24:25]
	v_pk_add_f32 v[52:53], v[52:53], v[26:27]
	v_pk_add_f32 v[52:53], v[52:53], v[28:29]
	v_pk_add_f32 v[52:53], v[52:53], v[30:31]
	v_pk_add_f32 v[52:53], v[52:53], v[32:33]
	v_pk_add_f32 v[52:53], v[52:53], v[34:35]
	v_pk_add_f32 v[52:53], v[52:53], v[36:37]
	v_pk_add_f32 v[52:53], v[52:53], v[38:39]
	v_pk_add_f32 v[52:53], v[52:53], v[40:41]
	v_pk_add_f32 v[52:53], v[52:53], v[42:43]
	v_pk_add_f32 v[52:53], v[52:53], v[44:45]
	v_pk_add_f32 v[52:53], v[52:53], v[46:47]
	v_pk_add_f32 v[52:53], v[52:53], v[48:49]
	v_pk_add_f32 v[52:53], v[52:53], v[50:51]
	s_branch .Lpp_w16_go

; __device__ __forceinline__ unsigned cvtpk(float lo, float hi) { return pg8::cvt_pk_bf16(lo, hi); }
; __device__ __forceinline__ float bflo(unsigned u) { return __uint_as_float(u << 16); }
; __device__ __forceinline__ float bfhi(unsigned u) { return __uint_as_float(u & 0xffff0000u); }
; __device__ __forceinline__ void pool_pre_phase(const bf16_t* hn, bf16_t* yp, int gtid, int ngt) {
;     ...
;         for (int tb = 0; tb < 64; tb += 16) {
; #pragma unroll
;             for (int i = 0; i < 16; ++i) { const int t = tb + i; const unsigned v = *(const unsigned*)(p + (size_t)t * DM);
;                 const float n0 = bflo(v), n1 = bfhi(v);
;                 const float o0 = r0[(i + 16 - w) & 15], o1 = r1[(i + 16 - w) & 15];
;                 s0 += n0 - o0; s1 += n1 - o1; r0[i] = n0; r1[i] = n1;
;                 const int cnt = (tr0 + t + 1 < w) ? (tr0 + t + 1) : w; const float inv = 1.0f / (float)cnt;
;                 *(unsigned*)(yp + (row0 + t) * DM + col) = cvtpk(s0 * inv - n0, s1 * inv - n1); }
.Lpp_w16_blk:
	s_mov_b32 s40, 0x3d800000
	s_mov_b32 s41, 0x3d800000
	s_mov_b32 s42, 0x3d800000
	s_mov_b32 s43, 0x3d800000
	s_mov_b32 s44, 0x3d800000
	s_mov_b32 s45, 0x3d800000
	s_mov_b32 s46, 0x3d800000
	s_mov_b32 s47, 0x3d800000
	s_mov_b32 s48, 0x3d800000
	s_mov_b32 s49, 0x3d800000
	s_mov_b32 s50, 0x3d800000
	s_mov_b32 s51, 0x3d800000
	s_mov_b32 s52, 0x3d800000
	s_mov_b32 s53, 0x3d800000
	s_mov_b32 s54, 0x3d800000
	s_mov_b32 s55, 0x3d800000
	s_or_b32 s66, s60, s61
	s_cmp_lg_u32 s66, 0
	s_cbranch_scc1 .Lpp_w16_ld
	s_mov_b32 s40, 0x3f800000
	s_mov_b32 s41, 0x3f000000
	s_mov_b32 s42, 0x3eaaaaab
	s_mov_b32 s43, 0x3e800000
	s_mov_b32 s44, 0x3e4ccccd
	s_mov_b32 s45, 0x3e2aaaab
	s_mov_b32 s46, 0x3e124925
	s_mov_b32 s47, 0x3e000000
	s_mov_b32 s48, 0x3de38e39
	s_mov_b32 s49, 0x3dcccccd
	s_mov_b32 s50, 0x3dba2e8c
	s_mov_b32 s51, 0x3daaaaab
	s_mov_b32 s52, 0x3d9d89d9
	s_mov_b32 s53, 0x3d924925
	s_mov_b32 s54, 0x3d888889
.Lpp_w16_ld:
	s_mov_b64 s[0:1], s[62:63]
	global_load_dword v62, v10, s[0:1]
	s_add_u32 s0, s0, 0x1000
	s_addc_u32 s1, s1, 0
	global_load_dword v63, v10, s[0:1]
	s_add_u32 s0, s0, 0x1000
	s_addc_u32 s1, s1, 0
	global_load_dword v64, v10, s[0:1]
	s_add_u32 s0, s0, 0x1000
	s_addc_u32 s1, s1, 0
	global_load_dword v65, v10, s[0:1]
	s_add_u32 s0, s0, 0x1000
	s_addc_u32 s1, s1, 0
	global_load_dword v66, v10, s[0:1]
	s_add_u32 s0, s0, 0x1000
	s_addc_u32 s1, s1, 0
	global_load_dword v67, v10, s[0:1]
	s_add_u32 s0, s0, 0x1000
	s_addc_u32 s1, s1, 0
	global_load_dword v68, v10, s[0:1]
	s_add_u32 s0, s0, 0x1000
	s_addc_u32 s1, s1, 0
	global_load_dword v69, v10, s[0:1]
	s_add_u32 s0, s0, 0x1000
	s_addc_u32 s1, s1, 0
	global_load_dword v70, v10, s[0:1]
	s_add_u32 s0, s0, 0x1000
	s_addc_u32 s1, s1, 0
	global_load_dword v71, v10, s[0:1]
	s_add_u32 s0, s0, 0x1000
	s_addc_u32 s1, s1, 0
	global_load_dword v72, v10, s[0:1]
	s_add_u32 s0, s0, 0x1000
	s_addc_u32 s1, s1, 0
	global_load_dword v73, v10, s[0:1]
	s_add_u32 s0, s0, 0x1000
	s_addc_u32 s1, s1, 0
	global_load_dword v74, v10, s[0:1]
	s_add_u32 s0, s0, 0x1000
	s_addc_u32 s1, s1, 0
	global_load_dword v75, v10, s[0:1]
	s_add_u32 s0, s0, 0x1000
	s_addc_u32 s1, s1, 0
	global_load_dword v76, v10, s[0:1]
	s_add_u32 s0, s0, 0x1000
	s_addc_u32 s1, s1, 0
	global_load_dword v77, v10, s[0:1]
	s_add_u32 s0, s0, 0x1000
	s_addc_u32 s1, s1, 0
	s_mov_b64 s[62:63], s[0:1]
	s_waitcnt vmcnt(15)
	v_lshlrev_b32_e32 v54, 16, v62
	v_and_b32_e32 v55, 0xffff0000, v62
	v_pk_add_f32 v[56:57], v[54:55], v[20:21] neg_lo:[0,1] neg_hi:[0,1]
	v_pk_add_f32 v[52:53], v[52:53], v[56:57]
	v_fma_f32 v58, s40, v52, -v54
	v_fma_f32 v59, s40, v53, -v55
	v_cvt_pk_bf16_f32 v60, v58, v59
	global_store_dword v10, v60, s[64:65]
	s_add_u32 s64, s64, 0x1000
	s_addc_u32 s65, s65, 0
	v_mov_b64_e32 v[20:21], v[54:55]
	s_waitcnt vmcnt(15)
	v_lshlrev_b32_e32 v54, 16, v63
	v_and_b32_e32 v55, 0xffff0000, v63
	v_pk_add_f32 v[56:57], v[54:55], v[22:23] neg_lo:[0,1] neg_hi:[0,1]
	v_pk_add_f32 v[52:53], v[52:53], v[56:57]
	v_fma_f32 v58, s41, v52, -v54
	v_fma_f32 v59, s41, v53, -v55
	v_cvt_pk_bf16_f32 v60, v58, v59
	global_store_dword v10, v60, s[64:65]
	s_add_u32 s64, s64, 0x1000
	s_addc_u32 s65, s65, 0
	v_mov_b64_e32 v[22:23], v[54:55]
	s_waitcnt vmcnt(15)
	v_lshlrev_b32_e32 v54, 16, v64
	v_and_b32_e32 v55, 0xffff0000, v64
	v_pk_add_f32 v[56:57], v[54:55], v[24:25] neg_lo:[0,1] neg_hi:[0,1]
	v_pk_add_f32 v[52:53], v[52:53], v[56:57]
	v_fma_f32 v58, s42, v52, -v54
	v_fma_f32 v59, s42, v53, -v55
	v_cvt_pk_bf16_f32 v60, v58, v59
	global_store_dword v10, v60, s[64:65]
	s_add_u32 s64, s64, 0x1000
	s_addc_u32 s65, s65, 0
	v_mov_b64_e32 v[24:25], v[54:55]
	s_waitcnt vmcnt(15)
	v_lshlrev_b32_e32 v54, 16, v65
	v_and_b32_e32 v55, 0xffff0000, v65
	v_pk_add_f32 v[56:57], v[54:55], v[26:27] neg_lo:[0,1] neg_hi:[0,1]
	v_pk_add_f32 v[52:53], v[52:53], v[56:57]
	v_fma_f32 v58, s43, v52, -v54
	v_fma_f32 v59, s43, v53, -v55
	v_cvt_pk_bf16_f32 v60, v58, v59
	global_store_dword v10, v60, s[64:65]
	s_add_u32 s64, s64, 0x1000
	s_addc_u32 s65, s65, 0
	v_mov_b64_e32 v[26:27], v[54:55]
	s_waitcnt vmcnt(15)
	v_lshlrev_b32_e32 v54, 16, v66
	v_and_b32_e32 v55, 0xffff0000, v66
	v_pk_add_f32 v[56:57], v[54:55], v[28:29] neg_lo:[0,1] neg_hi:[0,1]
	v_pk_add_f32 v[52:53], v[52:53], v[56:57]
	v_fma_f32 v58, s44, v52, -v54
	v_fma_f32 v59, s44, v53, -v55
	v_cvt_pk_bf16_f32 v60, v58, v59
	global_store_dword v10, v60, s[64:65]
	s_add_u32 s64, s64, 0x1000
	s_addc_u32 s65, s65, 0
	v_mov_b64_e32 v[28:29], v[54:55]
	s_waitcnt vmcnt(15)
	v_lshlrev_b32_e32 v54, 16, v67
	v_and_b32_e32 v55, 0xffff0000, v67
	v_pk_add_f32 v[56:57], v[54:55], v[30:31] neg_lo:[0,1] neg_hi:[0,1]
	v_pk_add_f32 v[52:53], v[52:53], v[56:57]
	v_fma_f32 v58, s45, v52, -v54
	v_fma_f32 v59, s45, v53, -v55
	v_cvt_pk_bf16_f32 v60, v58, v59
	global_store_dword v10, v60, s[64:65]
	s_add_u32 s64, s64, 0x1000
	s_addc_u32 s65, s65, 0
	v_mov_b64_e32 v[30:31], v[54:55]
	s_waitcnt vmcnt(15)
; __device__ __forceinline__ unsigned cvtpk(float lo, float hi) { return pg8::cvt_pk_bf16(lo, hi); }
; __device__ __forceinline__ float bflo(unsigned u) { return __uint_as_float(u << 16); }
; __device__ __forceinline__ float bfhi(unsigned u) { return __uint_as_float(u & 0xffff0000u); }
; __device__ __forceinline__ void pool_pre_phase(const bf16_t* hn, bf16_t* yp, int gtid, int ngt) {
;     ...
;         for (int tb = 0; tb < 64; tb += 16) {
; #pragma unroll
;             for (int i = 0; i < 16; ++i) { const int t = tb + i; const unsigned v = *(const unsigned*)(p + (size_t)t * DM);
;                 const float n0 = bflo(v), n1 = bfhi(v);
;                 const float o0 = r0[(i + 16 - w) & 15], o1 = r1[(i + 16 - w) & 15];
;                 s0 += n0 - o0; s1 += n1 - o1; r0[i] = n0; r1[i] = n1;
;                 const int cnt = (tr0 + t + 1 < w) ? (tr0 + t + 1) : w; const float inv = 1.0f / (float)cnt;
;                 *(unsigned*)(yp + (row0 + t) * DM + col) = cvtpk(s0 * inv - n0, s1 * inv - n1); }
;         }
;     }
	v_lshlrev_b32_e32 v54, 16, v68
	v_and_b32_e32 v55, 0xffff0000, v68
	v_pk_add_f32 v[56:57], v[54:55], v[32:33] neg_lo:[0,1] neg_hi:[0,1]
	v_pk_add_f32 v[52:53], v[52:53], v[56:57]
	v_fma_f32 v58, s46, v52, -v54
	v_fma_f32 v59, s46, v53, -v55
	v_cvt_pk_bf16_f32 v60, v58, v59
	global_store_dword v10, v60, s[64:65]
	s_add_u32 s64, s64, 0x1000
	s_addc_u32 s65, s65, 0
	v_mov_b64_e32 v[32:33], v[54:55]
	s_waitcnt vmcnt(15)
	v_lshlrev_b32_e32 v54, 16, v69
	v_and_b32_e32 v55, 0xffff0000, v69
	v_pk_add_f32 v[56:57], v[54:55], v[34:35] neg_lo:[0,1] neg_hi:[0,1]
	v_pk_add_f32 v[52:53], v[52:53], v[56:57]
	v_fma_f32 v58, s47, v52, -v54
	v_fma_f32 v59, s47, v53, -v55
	v_cvt_pk_bf16_f32 v60, v58, v59
	global_store_dword v10, v60, s[64:65]
	s_add_u32 s64, s64, 0x1000
	s_addc_u32 s65, s65, 0
	v_mov_b64_e32 v[34:35], v[54:55]
	s_waitcnt vmcnt(15)
	v_lshlrev_b32_e32 v54, 16, v70
	v_and_b32_e32 v55, 0xffff0000, v70
	v_pk_add_f32 v[56:57], v[54:55], v[36:37] neg_lo:[0,1] neg_hi:[0,1]
	v_pk_add_f32 v[52:53], v[52:53], v[56:57]
	v_fma_f32 v58, s48, v52, -v54
	v_fma_f32 v59, s48, v53, -v55
	v_cvt_pk_bf16_f32 v60, v58, v59
	global_store_dword v10, v60, s[64:65]
	s_add_u32 s64, s64, 0x1000
	s_addc_u32 s65, s65, 0
	v_mov_b64_e32 v[36:37], v[54:55]
	s_waitcnt vmcnt(15)
	v_lshlrev_b32_e32 v54, 16, v71
	v_and_b32_e32 v55, 0xffff0000, v71
	v_pk_add_f32 v[56:57], v[54:55], v[38:39] neg_lo:[0,1] neg_hi:[0,1]
	v_pk_add_f32 v[52:53], v[52:53], v[56:57]
	v_fma_f32 v58, s49, v52, -v54
	v_fma_f32 v59, s49, v53, -v55
	v_cvt_pk_bf16_f32 v60, v58, v59
	global_store_dword v10, v60, s[64:65]
	s_add_u32 s64, s64, 0x1000
	s_addc_u32 s65, s65, 0
	v_mov_b64_e32 v[38:39], v[54:55]
	s_waitcnt vmcnt(15)
	v_lshlrev_b32_e32 v54, 16, v72
	v_and_b32_e32 v55, 0xffff0000, v72
	v_pk_add_f32 v[56:57], v[54:55], v[40:41] neg_lo:[0,1] neg_hi:[0,1]
	v_pk_add_f32 v[52:53], v[52:53], v[56:57]
	v_fma_f32 v58, s50, v52, -v54
	v_fma_f32 v59, s50, v53, -v55
	v_cvt_pk_bf16_f32 v60, v58, v59
	global_store_dword v10, v60, s[64:65]
	s_add_u32 s64, s64, 0x1000
	s_addc_u32 s65, s65, 0
	v_mov_b64_e32 v[40:41], v[54:55]
	s_waitcnt vmcnt(15)
	v_lshlrev_b32_e32 v54, 16, v73
	v_and_b32_e32 v55, 0xffff0000, v73
	v_pk_add_f32 v[56:57], v[54:55], v[42:43] neg_lo:[0,1] neg_hi:[0,1]
	v_pk_add_f32 v[52:53], v[52:53], v[56:57]
	v_fma_f32 v58, s51, v52, -v54
	v_fma_f32 v59, s51, v53, -v55
	v_cvt_pk_bf16_f32 v60, v58, v59
	global_store_dword v10, v60, s[64:65]
	s_add_u32 s64, s64, 0x1000
	s_addc_u32 s65, s65, 0
	v_mov_b64_e32 v[42:43], v[54:55]
	s_waitcnt vmcnt(15)
	v_lshlrev_b32_e32 v54, 16, v74
	v_and_b32_e32 v55, 0xffff0000, v74
	v_pk_add_f32 v[56:57], v[54:55], v[44:45] neg_lo:[0,1] neg_hi:[0,1]
	v_pk_add_f32 v[52:53], v[52:53], v[56:57]
	v_fma_f32 v58, s52, v52, -v54
	v_fma_f32 v59, s52, v53, -v55
	v_cvt_pk_bf16_f32 v60, v58, v59
	global_store_dword v10, v60, s[64:65]
	s_add_u32 s64, s64, 0x1000
	s_addc_u32 s65, s65, 0
	v_mov_b64_e32 v[44:45], v[54:55]
	s_waitcnt vmcnt(15)
	v_lshlrev_b32_e32 v54, 16, v75
	v_and_b32_e32 v55, 0xffff0000, v75
	v_pk_add_f32 v[56:57], v[54:55], v[46:47] neg_lo:[0,1] neg_hi:[0,1]
	v_pk_add_f32 v[52:53], v[52:53], v[56:57]
	v_fma_f32 v58, s53, v52, -v54
	v_fma_f32 v59, s53, v53, -v55
	v_cvt_pk_bf16_f32 v60, v58, v59
	global_store_dword v10, v60, s[64:65]
	s_add_u32 s64, s64, 0x1000
	s_addc_u32 s65, s65, 0
	v_mov_b64_e32 v[46:47], v[54:55]
	s_waitcnt vmcnt(15)
	v_lshlrev_b32_e32 v54, 16, v76
	v_and_b32_e32 v55, 0xffff0000, v76
	v_pk_add_f32 v[56:57], v[54:55], v[48:49] neg_lo:[0,1] neg_hi:[0,1]
	v_pk_add_f32 v[52:53], v[52:53], v[56:57]
	v_fma_f32 v58, s54, v52, -v54
	v_fma_f32 v59, s54, v53, -v55
	v_cvt_pk_bf16_f32 v60, v58, v59
	global_store_dword v10, v60, s[64:65]
	s_add_u32 s64, s64, 0x1000
	s_addc_u32 s65, s65, 0
	v_mov_b64_e32 v[48:49], v[54:55]
	s_waitcnt vmcnt(15)
	v_lshlrev_b32_e32 v54, 16, v77
	v_and_b32_e32 v55, 0xffff0000, v77
	v_pk_add_f32 v[56:57], v[54:55], v[50:51] neg_lo:[0,1] neg_hi:[0,1]
	v_pk_add_f32 v[52:53], v[52:53], v[56:57]
	v_fma_f32 v58, s55, v52, -v54
	v_fma_f32 v59, s55, v53, -v55
	v_cvt_pk_bf16_f32 v60, v58, v59
	global_store_dword v10, v60, s[64:65]
	s_add_u32 s64, s64, 0x1000
	s_addc_u32 s65, s65, 0
	v_mov_b64_e32 v[50:51], v[54:55]
	s_add_i32 s61, s61, 1
	s_cmp_lt_u32 s61, 4
	s_cbranch_scc1 .Lpp_w16_blk
	s_branch .Lpp_next
.Lpp_next:
	v_readlane_b32 s0, v252, 49
	s_nop 1
	v_add_u32_e32 v9, s0, v9
	s_mov_b32 s0, 0x3ffff
	v_cmp_lt_i32_e32 vcc, s0, v9
	s_or_b64 s[20:21], vcc, s[20:21]
	s_andn2_b64 exec, exec, s[20:21]
	s_cbranch_execnz .Lpp_item
